# gdn_prep: dt_bias and a_log gate parameter loads issued at item start instead of two serialized round trips in wave 0
# baseline (speedup 1.0000x reference)
; #define LAS __attribute__((address_space(3)))
; DI void gdn_prep_item(const Args& a, int l, int bh, int n, LAS unsigned char* lds, const int tidx, const int xf) {
;     const int tid = tidx, lane = tid & 63, wave = tid >> 6, hf = lane >> 5;
;     const int b = bh / NH, h = bh % NH;
;     const size_t row0 = (size_t)b * SEQ + (size_t)n * 64;
;     const bf16_t* proj = (const bf16_t*)(a.ws + WS_PROJ);
;     const float* ab = (const float*)(a.ws + WS_AB);
;     float* egl = (float*)(a.ws + WS_EGL);
;     unsigned char* rec = a.ws + WS_GREC + (size_t)(bh * 64 + n) * REC_BYTES;
;     unsigned char* urec = a.ws + WS_UREC + (size_t)(bh * 64 + n) * 16384;
;     const float* convw = a.gdn_conv_w + (size_t)l * 4 * 2304;
;     int zoff; asm volatile("v_mov_b32 %0, 0" : "=v"(zoff));
;     LAS float* Mm = (LAS float*)(lds + zoff); LAS float* Ai = Mm + 64 * MM_LD; LAS float* gcs = Ai + 64 * MM_LD; LAS float* bts = gcs + 64; LAS float* bes = bts + 64; LAS float* kds = bes + 64; LAS float* egs = kds + 64;
;     LAS float* qs = egs + 64; LAS float* ks = qs + 64 * QS_LD; LAS float* vs = ks + 64 * QS_LD;
;     const float av = ab[(row0 + (tid & 63)) * 12 + h], bv = ab[(row0 + (tid & 63)) * 12 + 6 + h];
;     {
;         const int t = tid >> 3, cgp = tid & 7, tpos = n * 64 + t;
;         u32x4 raw[3][4][2];
; #pragma unroll
;         for (int sec = 0; sec < 3; ++sec)
; #pragma unroll
;             for (int tap = 0; tap < 4; ++tap) { const bool ok = (tpos - 3 + tap >= 0);
;                 const bf16_t* p = proj + (row0 + t - (ok ? 3 - tap : 0)) * NPROJ + C_GQ + sec * 768 + h * 128 + cgp * 16;
;                 raw[sec][tap][0] = *(const u32x4*)p; raw[sec][tap][1] = *(const u32x4*)(p + 8); }
;         __builtin_amdgcn_sched_barrier(0);
; #pragma unroll
;         for (int sec = 0; sec < 3; ++sec) {
;             const int wbase = sec * 768 + h * 128 + cgp * 16;
;             float acc[16];
; #pragma unroll
;             for (int c = 0; c < 16; ++c) acc[c] = 0.f;
;             f32x4 wv[4][4];
; #pragma unroll
;             for (int tap = 0; tap < 4; ++tap) {
;                 const bool ok = (tpos - 3 + tap >= 0);
;                 const f32x4* wp = (const f32x4*)(convw + tap * 2304 + wbase);
; #pragma unroll
;                 for (int c4 = 0; c4 < 4; ++c4) wv[tap][c4] = wp[c4];
;                 if (n == 0) { const float m = ok ? 1.f : 0.f;
; #pragma unroll
.LBB0_395:
	s_ashr_i32 s4, s35, 6
	s_mul_hi_i32 s22, s4, 0x2aaaaaab
	s_lshr_b32 s23, s22, 31
	s_add_i32 s22, s22, s23
	s_mul_i32 s23, s22, 6
	s_and_b32 s5, s35, 63
	s_sub_i32 s82, s4, s23
	s_ashr_i32 s23, s22, 31
	s_lshl_b64 s[22:23], s[22:23], 12
	s_lshl_b32 s4, s5, 6
	s_or_b32 s22, s22, s4
	v_add_u32_e32 v197, s4, v162
	v_or_b32_e32 v0, s22, v160
	v_cmp_gt_i32_e32 vcc, 3, v197
	v_mad_u64_u32 v[0:1], s[24:25], v0, 48, s[36:37]
	v_lshl_add_u64 v[2:3], s[22:23], 0, v[162:163]
	v_cndmask_b32_e64 v5, -1, 0, vcc
	v_cndmask_b32_e64 v4, -3, 0, vcc
	s_lshl_b32 s24, s82, 7
	v_lshl_add_u64 v[4:5], v[2:3], 0, v[4:5]
	v_mov_b64_e32 v[6:7], s[58:59]
	v_mad_i32_i24 v1, s23, 48, v1
	s_ashr_i32 s25, s24, 31
	v_mad_u64_u32 v[8:9], s[22:23], v4, s47, v[6:7]
	v_mad_i32_i24 v9, v5, s47, v9
	s_lshl_b64 s[26:27], s[24:25], 1
	v_lshlrev_b32_e32 v204, 1, v164
	v_lshl_add_u64 v[4:5], v[8:9], 0, s[26:27]
	v_lshl_add_u64 v[4:5], v[4:5], 0, v[204:205]
	s_mov_b32 s4, 0x7d02000
	v_add_co_u32_e32 v10, vcc, s4, v4
	s_ashr_i32 s83, s82, 31
	s_nop 0
	v_addc_co_u32_e32 v11, vcc, 0, v5, vcc
	v_lshl_add_u64 v[0:1], s[82:83], 2, v[0:1]
	s_mov_b64 s[30:31], 0x7d02400
	v_cmp_gt_i32_e32 vcc, 2, v197
	v_mov_b32 v194, 0
	v_lshl_add_u64 v[8:9], v[4:5], 0, s[30:31]
	s_add_i32 s98, s82, s97
	s_ashr_i32 s99, s98, 31
	s_lshl_b64 s[98:99], s[98:99], 2
	s_add_u32 s100, s72, s98
	s_addc_u32 s101, s73, s99
	global_load_dword v200, v205, s[100:101]
	s_add_u32 s98, s70, s98
	s_addc_u32 s99, s71, s99
	global_load_dword v201, v205, s[98:99]
	global_load_dword v196, v[0:1], off
	global_load_dword v195, v[0:1], off offset:24
	global_load_dwordx4 v[64:67], v[8:9], off offset:16
	v_cndmask_b32_e64 v1, -1, 0, vcc
	v_cndmask_b32_e64 v0, -2, 0, vcc
	v_lshl_add_u64 v[0:1], v[2:3], 0, v[0:1]
	v_mad_u64_u32 v[8:9], s[22:23], v0, s47, v[6:7]
	v_mad_i32_i24 v9, v1, s47, v9
	v_lshl_add_u64 v[0:1], v[8:9], 0, s[26:27]
	v_lshl_add_u64 v[0:1], v[0:1], 0, v[204:205]
	v_add_co_u32_e32 v12, vcc, s4, v0
	v_lshl_add_u64 v[8:9], v[0:1], 0, s[30:31]
	s_nop 0
	v_addc_co_u32_e32 v13, vcc, 0, v1, vcc
	v_cmp_lt_i32_e64 s[22:23], 0, v197
	global_load_dwordx4 v[92:95], v[12:13], off offset:1024
	global_load_dwordx4 v[68:71], v[8:9], off offset:16
	v_cndmask_b32_e64 v8, 0, 1, s[22:23]
	v_sub_co_u32_e32 v8, vcc, v2, v8
	v_mad_u64_u32 v[8:9], s[28:29], v8, s47, v[6:7]
	s_nop 0
	v_subbrev_co_u32_e32 v14, vcc, 0, v3, vcc
	v_mad_i32_i24 v9, v14, s47, v9
	v_lshl_add_u64 v[8:9], v[8:9], 0, s[26:27]
	v_mad_u64_u32 v[6:7], s[28:29], v2, s47, v[6:7]
	v_lshl_add_u64 v[8:9], v[8:9], 0, v[204:205]
	v_mad_i32_i24 v7, v3, s47, v7
	v_add_co_u32_e32 v16, vcc, s4, v8
	v_lshl_add_u64 v[2:3], v[6:7], 0, s[26:27]
	s_nop 0
	v_addc_co_u32_e32 v17, vcc, 0, v9, vcc
	v_lshl_add_u64 v[28:29], v[2:3], 0, v[204:205]
	v_add_co_u32_e32 v6, vcc, s4, v28
	s_mov_b64 s[26:27], 0x7d02a00
	s_nop 0
	v_addc_co_u32_e32 v7, vcc, 0, v29, vcc
	v_lshl_add_u64 v[14:15], v[8:9], 0, s[30:31]
	v_lshl_add_u64 v[2:3], v[28:29], 0, s[30:31]
	global_load_dwordx4 v[96:99], v[6:7], off offset:1024
	global_load_dwordx4 v[72:75], v[2:3], off offset:16
	global_load_dwordx4 v[104:107], v[10:11], off offset:1024
	global_load_dwordx4 v[60:63], v[10:11], off offset:2560
	v_lshl_add_u64 v[10:11], v[0:1], 0, s[26:27]
	v_lshl_add_u64 v[2:3], v[4:5], 0, s[26:27]
	global_load_dwordx4 v[76:79], v[14:15], off offset:16
	global_load_dwordx4 v[56:59], v[12:13], off offset:2560
	v_lshl_add_u64 v[12:13], v[8:9], 0, s[26:27]
	global_load_dwordx4 v[100:103], v[16:17], off offset:1024
	global_load_dwordx4 v[52:55], v[16:17], off offset:2560
	global_load_dwordx4 v[40:43], v[10:11], off offset:16
	global_load_dwordx4 v[32:35], v[12:13], off offset:16
	v_lshl_add_u64 v[10:11], v[28:29], 0, s[26:27]
	s_mov_b64 s[26:27], 0x7d03000
	s_mov_b32 s4, 0x7d03000
	global_load_dwordx4 v[44:47], v[2:3], off offset:16
	global_load_dwordx4 v[48:51], v[6:7], off offset:2560
	v_lshl_add_u64 v[2:3], v[4:5], 0, s[26:27]
	v_add_co_u32_e32 v4, vcc, s4, v4
	global_load_dwordx4 v[36:39], v[10:11], off offset:16
	global_load_dwordx4 v[16:19], v[2:3], off offset:16
	v_addc_co_u32_e32 v5, vcc, 0, v5, vcc
	v_add_co_u32_e32 v10, vcc, s4, v0
	v_lshl_add_u64 v[12:13], v[8:9], 0, s[26:27]
	s_nop 0
	v_addc_co_u32_e32 v11, vcc, 0, v1, vcc
	v_add_co_u32_e32 v14, vcc, s4, v8
	v_lshl_add_u64 v[6:7], v[0:1], 0, s[26:27]
	s_nop 0
	v_addc_co_u32_e32 v15, vcc, 0, v9, vcc
	v_add_co_u32_e32 v8, vcc, s4, v28
	v_lshl_add_u64 v[30:31], v[28:29], 0, s[26:27]
	s_nop 0
	v_addc_co_u32_e32 v9, vcc, 0, v29, vcc
	global_load_dwordx4 v[0:3], v[4:5], off
	global_load_dwordx4 v[20:23], v[6:7], off offset:16
	s_nop 0
	global_load_dwordx4 v[4:7], v[10:11], off
	global_load_dwordx4 v[24:27], v[12:13], off offset:16
	s_nop 0
	global_load_dwordx4 v[8:11], v[8:9], off
	s_nop 0
	global_load_dwordx4 v[12:15], v[14:15], off
	s_nop 0
	global_load_dwordx4 v[28:31], v[30:31], off offset:16
	s_waitcnt vmcnt(0)
	v_or_b32_e32 v80, s24, v164
	v_ashrrev_i32_e32 v81, 31, v80
	v_lshl_add_u64 v[174:175], v[80:81], 2, s[0:1]
	global_load_dwordx4 v[144:147], v[174:175], off offset:48
	global_load_dwordx4 v[80:83], v[174:175], off offset:32
	global_load_dwordx4 v[112:115], v[174:175], off offset:16
	global_load_dwordx4 v[128:131], v[174:175], off
	s_cmp_eq_u32 s5, 0
	s_cselect_b64 s[28:29], -1, 0
	s_cmp_lg_u32 s5, 0
	v_cmp_lt_i32_e64 s[26:27], 2, v197
	s_cbranch_scc1 .LBB0_397
	s_waitcnt vmcnt(36)
	v_cndmask_b32_e64 v84, 0, 1.0, s[26:27]
	s_waitcnt vmcnt(0)
	v_pk_mul_f32 v[130:131], v[84:85], v[130:131] op_sel_hi:[0,1]
	v_pk_mul_f32 v[128:129], v[84:85], v[128:129] op_sel_hi:[0,1]
	v_pk_mul_f32 v[114:115], v[84:85], v[114:115] op_sel_hi:[0,1]
	v_pk_mul_f32 v[112:113], v[84:85], v[112:113] op_sel_hi:[0,1]
	v_pk_mul_f32 v[82:83], v[84:85], v[82:83] op_sel_hi:[0,1]
	v_pk_mul_f32 v[80:81], v[84:85], v[80:81] op_sel_hi:[0,1]
	v_pk_mul_f32 v[146:147], v[84:85], v[146:147] op_sel_hi:[0,1]
	v_pk_mul_f32 v[144:145], v[84:85], v[144:145] op_sel_hi:[0,1]

; #define LAS __attribute__((address_space(3)))
; DI float sum8(float v) { v += dpp_f(v, 0); v += dpp_f(v, 1); v += dpp_f(v, 2); return v; }
; DI void gdn_prep_item(const Args& a, int l, int bh, int n, LAS unsigned char* lds, const int tidx, const int xf) {
;     ...
;             for (int tap = 0; tap < 4; ++tap) {
;                 const u32x4 ra = raw[sec][tap][0], rb = raw[sec][tap][1];
;                 const float u[16] = {bflo(ra.x), bfhi(ra.x), bflo(ra.y), bfhi(ra.y), bflo(ra.z), bfhi(ra.z), bflo(ra.w), bfhi(ra.w),
;                                      bflo(rb.x), bfhi(rb.x), bflo(rb.y), bfhi(rb.y), bflo(rb.z), bfhi(rb.z), bflo(rb.w), bfhi(rb.w)};
; #pragma unroll
;                 for (int c4 = 0; c4 < 4; ++c4) { const f32x4 w = wv[tap][c4]; acc[4 * c4] += w.x * u[4 * c4]; acc[4 * c4 + 1] += w.y * u[4 * c4 + 1]; acc[4 * c4 + 2] += w.z * u[4 * c4 + 2]; acc[4 * c4 + 3] += w.w * u[4 * c4 + 3]; }
;             }
;             float ss = 0.f;
; #pragma unroll
;             for (int c = 0; c < 16; ++c) { acc[c] = acc[c] / (1.f + __expf(-acc[c])); ss += acc[c] * acc[c]; }
;             float sc = 1.f;
;             if (sec < 2) { ss = sum8(ss); sc = rsqrtf(ss + 1e-6f) * (sec == 0 ? 0.08838834764831845f : 1.f); }
;             LAS float* dst = (sec == 0 ? qs : (sec == 1 ? ks : vs)) + t * QS_LD + cgp * 16;
; #pragma unroll
;             for (int c4 = 0; c4 < 4; ++c4) *(LAS f32x4*)(dst + 4 * c4) = (f32x4){acc[4 * c4] * sc, acc[4 * c4 + 1] * sc, acc[4 * c4 + 2] * sc, acc[4 * c4 + 3] * sc};
.LBB0_419:
	v_lshlrev_b32_e32 v98, 16, v19
	v_and_b32_e32 v99, 0xffff0000, v19
	s_waitcnt vmcnt(14)
	v_pk_fma_f32 v[50:51], v[50:51], v[98:99], 0 op_sel_hi:[1,1,0]
	v_lshlrev_b32_e32 v98, 16, v23
	v_and_b32_e32 v99, 0xffff0000, v23
	s_waitcnt vmcnt(10)
	v_pk_fma_f32 v[50:51], v[74:75], v[98:99], v[50:51]
	v_lshlrev_b32_e32 v74, 16, v27
	v_and_b32_e32 v75, 0xffff0000, v27
	s_waitcnt vmcnt(6)
	v_pk_fma_f32 v[50:51], v[86:87], v[74:75], v[50:51]
	v_lshlrev_b32_e32 v74, 16, v31
	v_and_b32_e32 v75, 0xffff0000, v31
	s_waitcnt vmcnt(2)
	v_pk_fma_f32 v[50:51], v[94:95], v[74:75], v[50:51]
	v_lshlrev_b32_e32 v86, 16, v18
	v_mul_f32_e32 v19, 0xbfb8aa3b, v51
	v_exp_f32_e32 v75, v19
	v_mul_f32_e32 v19, 0xbfb8aa3b, v50
	v_and_b32_e32 v87, 0xffff0000, v18
	v_exp_f32_e32 v74, v19
	v_pk_fma_f32 v[18:19], v[48:49], v[86:87], 0 op_sel_hi:[1,1,0]
	v_lshlrev_b32_e32 v48, 16, v22
	v_and_b32_e32 v49, 0xffff0000, v22
	v_pk_fma_f32 v[18:19], v[72:73], v[48:49], v[18:19]
	v_lshlrev_b32_e32 v22, 16, v26
	v_and_b32_e32 v23, 0xffff0000, v26
	v_lshlrev_b32_e32 v26, 16, v17
	v_and_b32_e32 v27, 0xffff0000, v17
	v_pk_fma_f32 v[18:19], v[84:85], v[22:23], v[18:19]
	v_lshlrev_b32_e32 v22, 16, v30
	v_and_b32_e32 v23, 0xffff0000, v30
	v_pk_fma_f32 v[26:27], v[42:43], v[26:27], 0 op_sel_hi:[1,1,0]
	v_lshlrev_b32_e32 v30, 16, v21
	v_and_b32_e32 v31, 0xffff0000, v21
	v_pk_fma_f32 v[26:27], v[62:63], v[30:31], v[26:27]
	v_lshlrev_b32_e32 v30, 16, v25
	v_and_b32_e32 v31, 0xffff0000, v25
	v_pk_fma_f32 v[26:27], v[78:79], v[30:31], v[26:27]
	v_lshlrev_b32_e32 v30, 16, v29
	v_and_b32_e32 v31, 0xffff0000, v29
	s_waitcnt vmcnt(1)
	v_pk_fma_f32 v[26:27], v[90:91], v[30:31], v[26:27]
	v_lshlrev_b32_e32 v42, 16, v16
	v_mul_f32_e32 v17, 0xbfb8aa3b, v27
	v_exp_f32_e32 v31, v17
	v_mul_f32_e32 v17, 0xbfb8aa3b, v26
	v_and_b32_e32 v43, 0xffff0000, v16
	v_exp_f32_e32 v30, v17
	v_pk_fma_f32 v[16:17], v[40:41], v[42:43], 0 op_sel_hi:[1,1,0]
	v_lshlrev_b32_e32 v40, 16, v20
	v_and_b32_e32 v41, 0xffff0000, v20
	v_pk_fma_f32 v[16:17], v[60:61], v[40:41], v[16:17]
	v_lshlrev_b32_e32 v20, 16, v24
	v_and_b32_e32 v21, 0xffff0000, v24
	v_lshlrev_b32_e32 v24, 16, v3
	v_and_b32_e32 v25, 0xffff0000, v3
	v_pk_fma_f32 v[16:17], v[76:77], v[20:21], v[16:17]
	v_lshlrev_b32_e32 v20, 16, v28
	v_and_b32_e32 v21, 0xffff0000, v28
	v_pk_fma_f32 v[24:25], v[38:39], v[24:25], 0 op_sel_hi:[1,1,0]
	v_lshlrev_b32_e32 v28, 16, v7
	v_and_b32_e32 v29, 0xffff0000, v7
	v_pk_fma_f32 v[24:25], v[54:55], v[28:29], v[24:25]
	v_lshlrev_b32_e32 v28, 16, v15
	v_and_b32_e32 v29, 0xffff0000, v15
	v_pk_fma_f32 v[24:25], v[66:67], v[28:29], v[24:25]
	v_lshlrev_b32_e32 v28, 16, v11
	v_and_b32_e32 v29, 0xffff0000, v11
	s_waitcnt vmcnt(0)
	v_pk_fma_f32 v[24:25], v[82:83], v[28:29], v[24:25]
	v_lshlrev_b32_e32 v38, 16, v2
	v_mul_f32_e32 v3, 0xbfb8aa3b, v25
	v_exp_f32_e32 v29, v3
	v_mul_f32_e32 v3, 0xbfb8aa3b, v24
	v_and_b32_e32 v39, 0xffff0000, v2
	v_exp_f32_e32 v28, v3
	v_pk_fma_f32 v[2:3], v[36:37], v[38:39], 0 op_sel_hi:[1,1,0]
	v_lshlrev_b32_e32 v36, 16, v6
	v_and_b32_e32 v37, 0xffff0000, v6
	v_pk_fma_f32 v[2:3], v[52:53], v[36:37], v[2:3]
	v_lshlrev_b32_e32 v6, 16, v14
	v_and_b32_e32 v7, 0xffff0000, v14
	v_pk_fma_f32 v[2:3], v[64:65], v[6:7], v[2:3]
	v_lshlrev_b32_e32 v6, 16, v10
	v_and_b32_e32 v7, 0xffff0000, v10
	v_pk_fma_f32 v[2:3], v[80:81], v[6:7], v[2:3]
	v_and_b32_e32 v7, 0xffff0000, v1
	v_mul_f32_e32 v6, 0xbfb8aa3b, v3
	v_exp_f32_e32 v11, v6
	v_mul_f32_e32 v6, 0xbfb8aa3b, v2
	v_exp_f32_e32 v10, v6
	v_lshlrev_b32_e32 v6, 16, v1
	v_pk_fma_f32 v[6:7], v[34:35], v[6:7], 0 op_sel_hi:[1,1,0]
	v_lshlrev_b32_e32 v14, 16, v5
	v_and_b32_e32 v15, 0xffff0000, v5
	v_pk_fma_f32 v[6:7], v[46:47], v[14:15], v[6:7]
	v_lshlrev_b32_e32 v14, 16, v13
	v_and_b32_e32 v15, 0xffff0000, v13
	v_pk_fma_f32 v[6:7], v[58:59], v[14:15], v[6:7]
	v_lshlrev_b32_e32 v14, 16, v9
	v_and_b32_e32 v15, 0xffff0000, v9
	v_pk_fma_f32 v[6:7], v[70:71], v[14:15], v[6:7]
	v_lshlrev_b32_e32 v34, 16, v0
	v_mul_f32_e32 v1, 0xbfb8aa3b, v7
	v_exp_f32_e32 v15, v1
	v_mul_f32_e32 v1, 0xbfb8aa3b, v6
	v_exp_f32_e32 v14, v1
	v_and_b32_e32 v35, 0xffff0000, v0
	v_pk_fma_f32 v[0:1], v[32:33], v[34:35], 0 op_sel_hi:[1,1,0]
	v_lshlrev_b32_e32 v32, 16, v4
	v_and_b32_e32 v33, 0xffff0000, v4
	v_pk_fma_f32 v[0:1], v[44:45], v[32:33], v[0:1]
	v_lshlrev_b32_e32 v4, 16, v12
	v_and_b32_e32 v5, 0xffff0000, v12
	v_pk_fma_f32 v[0:1], v[56:57], v[4:5], v[0:1]
	v_lshlrev_b32_e32 v4, 16, v8
	v_and_b32_e32 v5, 0xffff0000, v8
	v_pk_add_f32 v[12:13], v[14:15], 1.0 op_sel_hi:[1,0]
	v_pk_fma_f32 v[4:5], v[68:69], v[4:5], v[0:1]
	v_div_scale_f32 v1, s[4:5], v13, v13, v7
	v_rcp_f32_e32 v14, v1
	v_mul_f32_e32 v0, 0xbfb8aa3b, v5
	v_exp_f32_e32 v9, v0
	v_mul_f32_e32 v0, 0xbfb8aa3b, v4
	v_fma_f32 v15, -v1, v14, 1.0
	v_fmac_f32_e32 v14, v15, v14
	v_div_scale_f32 v15, vcc, v7, v13, v7
	v_mul_f32_e32 v32, v15, v14
	v_fma_f32 v33, -v1, v32, v15
	v_fmac_f32_e32 v32, v33, v14
	v_fma_f32 v1, -v1, v32, v15
	v_div_fmas_f32 v1, v1, v14, v32
	v_div_fixup_f32 v7, v1, v13, v7
	v_div_scale_f32 v1, s[4:5], v12, v12, v6
	v_rcp_f32_e32 v13, v1
	v_exp_f32_e32 v8, v0
	v_add_u32_e32 v97, 0x19500, v194
	v_add3_u32 v0, v97, v161, v146
	v_fma_f32 v14, -v1, v13, 1.0
	v_fmac_f32_e32 v13, v14, v13
	v_div_scale_f32 v14, vcc, v6, v12, v6
	v_mul_f32_e32 v15, v14, v13
	v_fma_f32 v32, -v1, v15, v14
	v_fmac_f32_e32 v15, v32, v13
	v_fma_f32 v1, -v1, v15, v14
	v_pk_add_f32 v[8:9], v[8:9], 1.0 op_sel_hi:[1,0]
	v_div_fmas_f32 v1, v1, v13, v15
	v_div_fixup_f32 v6, v1, v12, v6
	v_div_scale_f32 v1, s[4:5], v9, v9, v5
	v_rcp_f32_e32 v12, v1
	v_pk_fma_f32 v[16:17], v[88:89], v[20:21], v[16:17]
	v_pk_fma_f32 v[18:19], v[92:93], v[22:23], v[18:19]
; #define LAS __attribute__((address_space(3)))
; DI float sum8(float v) { v += dpp_f(v, 0); v += dpp_f(v, 1); v += dpp_f(v, 2); return v; }
; DI void gdn_prep_item(const Args& a, int l, int bh, int n, LAS unsigned char* lds, const int tidx, const int xf) {
;     ...
;             for (int c = 0; c < 16; ++c) { acc[c] = acc[c] / (1.f + __expf(-acc[c])); ss += acc[c] * acc[c]; }
;             float sc = 1.f;
;             if (sec < 2) { ss = sum8(ss); sc = rsqrtf(ss + 1e-6f) * (sec == 0 ? 0.08838834764831845f : 1.f); }
;             LAS float* dst = (sec == 0 ? qs : (sec == 1 ? ks : vs)) + t * QS_LD + cgp * 16;
; #pragma unroll
;             for (int c4 = 0; c4 < 4; ++c4) *(LAS f32x4*)(dst + 4 * c4) = (f32x4){acc[4 * c4] * sc, acc[4 * c4 + 1] * sc, acc[4 * c4 + 2] * sc, acc[4 * c4 + 3] * sc};
;         }
;     }
;     if (tid < 64) {
;         const float xx = av + a.gdn_dt_bias[l * NH + h];
	v_mul_f32_e32 v20, 0xbfb8aa3b, v17
	v_fma_f32 v13, -v1, v12, 1.0
	v_fmac_f32_e32 v12, v13, v12
	v_div_scale_f32 v13, vcc, v5, v9, v5
	v_mul_f32_e32 v14, v13, v12
	v_fma_f32 v15, -v1, v14, v13
	v_fmac_f32_e32 v14, v15, v12
	v_fma_f32 v1, -v1, v14, v13
	v_div_fmas_f32 v1, v1, v12, v14
	v_div_fixup_f32 v5, v1, v9, v5
	v_div_scale_f32 v1, s[4:5], v8, v8, v4
	v_rcp_f32_e32 v9, v1
	v_exp_f32_e32 v21, v20
	v_mul_f32_e32 v20, 0xbfb8aa3b, v16
	v_exp_f32_e32 v20, v20
	v_fma_f32 v12, -v1, v9, 1.0
	v_fmac_f32_e32 v9, v12, v9
	v_div_scale_f32 v12, vcc, v4, v8, v4
	v_mul_f32_e32 v13, v12, v9
	v_fma_f32 v14, -v1, v13, v12
	v_fmac_f32_e32 v13, v14, v9
	v_fma_f32 v1, -v1, v13, v12
	v_div_fmas_f32 v1, v1, v9, v13
	v_div_fixup_f32 v4, v1, v8, v4
	ds_write_b128 v0, v[4:7]
	v_pk_add_f32 v[4:5], v[28:29], 1.0 op_sel_hi:[1,0]
	v_pk_add_f32 v[6:7], v[10:11], 1.0 op_sel_hi:[1,0]
	v_div_scale_f32 v1, s[4:5], v5, v5, v25
	v_rcp_f32_e32 v8, v1
	v_mul_f32_e32 v22, 0xbfb8aa3b, v19
	v_exp_f32_e32 v23, v22
	v_mul_f32_e32 v22, 0xbfb8aa3b, v18
	v_fma_f32 v9, -v1, v8, 1.0
	v_fmac_f32_e32 v8, v9, v8
	v_div_scale_f32 v9, vcc, v25, v5, v25
	v_mul_f32_e32 v10, v9, v8
	v_fma_f32 v11, -v1, v10, v9
	v_fmac_f32_e32 v10, v11, v8
	v_fma_f32 v1, -v1, v10, v9
	v_div_fmas_f32 v1, v1, v8, v10
	v_div_fixup_f32 v5, v1, v5, v25
	v_div_scale_f32 v1, s[4:5], v4, v4, v24
	v_rcp_f32_e32 v8, v1
	v_exp_f32_e32 v22, v22
	v_fma_f32 v9, -v1, v8, 1.0
	v_fmac_f32_e32 v8, v9, v8
	v_div_scale_f32 v9, vcc, v24, v4, v24
	v_mul_f32_e32 v10, v9, v8
	v_fma_f32 v11, -v1, v10, v9
	v_fmac_f32_e32 v10, v11, v8
	v_fma_f32 v1, -v1, v10, v9
	v_div_fmas_f32 v1, v1, v8, v10
	v_div_fixup_f32 v4, v1, v4, v24
	v_div_scale_f32 v1, s[4:5], v7, v7, v3
	v_rcp_f32_e32 v8, v1
	s_nop 0
	v_fma_f32 v9, -v1, v8, 1.0
	v_fmac_f32_e32 v8, v9, v8
	v_div_scale_f32 v9, vcc, v3, v7, v3
	v_mul_f32_e32 v10, v9, v8
	v_fma_f32 v11, -v1, v10, v9
	v_fmac_f32_e32 v10, v11, v8
	v_fma_f32 v1, -v1, v10, v9
	v_div_fmas_f32 v1, v1, v8, v10
	v_div_fixup_f32 v3, v1, v7, v3
	v_div_scale_f32 v1, s[4:5], v6, v6, v2
	v_rcp_f32_e32 v7, v1
	s_nop 0
	v_fma_f32 v8, -v1, v7, 1.0
	v_fmac_f32_e32 v7, v8, v7
	v_div_scale_f32 v8, vcc, v2, v6, v2
	v_mul_f32_e32 v9, v8, v7
	v_fma_f32 v10, -v1, v9, v8
	v_fmac_f32_e32 v9, v10, v7
	v_fma_f32 v1, -v1, v9, v8
	v_div_fmas_f32 v1, v1, v7, v9
	v_div_fixup_f32 v2, v1, v6, v2
	ds_write_b128 v0, v[2:5] offset:16
	v_pk_add_f32 v[2:3], v[30:31], 1.0 op_sel_hi:[1,0]
	v_pk_add_f32 v[6:7], v[20:21], 1.0 op_sel_hi:[1,0]
	v_div_scale_f32 v1, s[4:5], v3, v3, v27
	v_rcp_f32_e32 v4, v1
	s_nop 0
	v_fma_f32 v5, -v1, v4, 1.0
	v_fmac_f32_e32 v4, v5, v4
	v_div_scale_f32 v5, vcc, v27, v3, v27
	v_mul_f32_e32 v8, v5, v4
	v_fma_f32 v9, -v1, v8, v5
	v_fmac_f32_e32 v8, v9, v4
	v_fma_f32 v1, -v1, v8, v5
	v_div_fmas_f32 v1, v1, v4, v8
	v_div_fixup_f32 v5, v1, v3, v27
	v_div_scale_f32 v1, s[4:5], v2, v2, v26
	v_rcp_f32_e32 v3, v1
	s_nop 0
	v_fma_f32 v4, -v1, v3, 1.0
	v_fmac_f32_e32 v3, v4, v3
	v_div_scale_f32 v4, vcc, v26, v2, v26
	v_mul_f32_e32 v8, v4, v3
	v_fma_f32 v9, -v1, v8, v4
	v_fmac_f32_e32 v8, v9, v3
	v_fma_f32 v1, -v1, v8, v4
	v_div_fmas_f32 v1, v1, v3, v8
	v_div_fixup_f32 v4, v1, v2, v26
	v_div_scale_f32 v1, s[4:5], v7, v7, v17
	v_rcp_f32_e32 v2, v1
	s_nop 0
	v_fma_f32 v3, -v1, v2, 1.0
	v_fmac_f32_e32 v2, v3, v2
	v_div_scale_f32 v3, vcc, v17, v7, v17
	v_mul_f32_e32 v8, v3, v2
	v_fma_f32 v9, -v1, v8, v3
	v_fmac_f32_e32 v8, v9, v2
	v_fma_f32 v1, -v1, v8, v3
	v_div_fmas_f32 v1, v1, v2, v8
	v_div_fixup_f32 v3, v1, v7, v17
	v_div_scale_f32 v1, s[4:5], v6, v6, v16
	v_rcp_f32_e32 v2, v1
	s_nop 0
	v_fma_f32 v7, -v1, v2, 1.0
	v_fmac_f32_e32 v2, v7, v2
	v_div_scale_f32 v7, vcc, v16, v6, v16
	v_mul_f32_e32 v8, v7, v2
	v_fma_f32 v9, -v1, v8, v7
	v_fmac_f32_e32 v8, v9, v2
	v_fma_f32 v1, -v1, v8, v7
	v_div_fmas_f32 v1, v1, v2, v8
	v_div_fixup_f32 v2, v1, v6, v16
	ds_write_b128 v0, v[2:5] offset:32
	v_pk_add_f32 v[2:3], v[74:75], 1.0 op_sel_hi:[1,0]
	v_pk_add_f32 v[6:7], v[22:23], 1.0 op_sel_hi:[1,0]
	v_div_scale_f32 v1, s[4:5], v3, v3, v51
	v_rcp_f32_e32 v4, v1
	s_nop 0
	v_fma_f32 v5, -v1, v4, 1.0
	v_fmac_f32_e32 v4, v5, v4
	v_div_scale_f32 v5, vcc, v51, v3, v51
	v_mul_f32_e32 v8, v5, v4
	v_fma_f32 v9, -v1, v8, v5
	v_fmac_f32_e32 v8, v9, v4
	v_fma_f32 v1, -v1, v8, v5
	v_div_fmas_f32 v1, v1, v4, v8
	v_div_fixup_f32 v5, v1, v3, v51
	v_div_scale_f32 v1, s[4:5], v2, v2, v50
	v_rcp_f32_e32 v3, v1
	s_nop 0
	v_fma_f32 v4, -v1, v3, 1.0
	v_fmac_f32_e32 v3, v4, v3
	v_div_scale_f32 v4, vcc, v50, v2, v50
	v_mul_f32_e32 v8, v4, v3
	v_fma_f32 v9, -v1, v8, v4
	v_fmac_f32_e32 v8, v9, v3
	v_fma_f32 v1, -v1, v8, v4
	v_div_fmas_f32 v1, v1, v3, v8
	v_div_fixup_f32 v4, v1, v2, v50
	v_div_scale_f32 v1, s[4:5], v7, v7, v19
	v_rcp_f32_e32 v2, v1
	s_nop 0
	v_fma_f32 v3, -v1, v2, 1.0
	v_fmac_f32_e32 v2, v3, v2
	v_div_scale_f32 v3, vcc, v19, v7, v19
	v_mul_f32_e32 v8, v3, v2
	v_fma_f32 v9, -v1, v8, v3
	v_fmac_f32_e32 v8, v9, v2
	v_fma_f32 v1, -v1, v8, v3
	v_div_fmas_f32 v1, v1, v2, v8
	v_div_fixup_f32 v3, v1, v7, v19
	v_div_scale_f32 v1, s[4:5], v6, v6, v18
	v_rcp_f32_e32 v2, v1
	s_nop 0
	v_fma_f32 v7, -v1, v2, 1.0
	v_fmac_f32_e32 v2, v7, v2
	v_div_scale_f32 v7, vcc, v18, v6, v18
	v_mul_f32_e32 v8, v7, v2
	v_fma_f32 v9, -v1, v8, v7
	v_fmac_f32_e32 v8, v9, v2
	v_fma_f32 v1, -v1, v8, v7
	v_div_fmas_f32 v1, v1, v2, v8
	v_div_fixup_f32 v2, v1, v6, v18
	ds_write_b128 v0, v[2:5] offset:48
	s_and_saveexec_b64 s[22:23], s[38:39]
	s_cbranch_execz .LBB0_424
	s_add_i32 s4, s82, s97
	s_ashr_i32 s5, s4, 31
	s_lshl_b64 s[24:25], s[4:5], 2
	s_add_u32 s4, s72, s24
	s_addc_u32 s5, s73, s25
	v_mov_b32_e32 v0, v200
	s_mov_b32 s4, 0x41a00000
	s_waitcnt vmcnt(0)
	v_add_f32_e32 v0, v196, v0
	v_cmp_nlt_f32_e32 vcc, s4, v0
	s_and_saveexec_b64 s[26:27], vcc
	s_cbranch_execz .LBB0_422
; DI void gdn_prep_item(const Args& a, int l, int bh, int n, LAS unsigned char* lds, const int tidx, const int xf) {
;     ...
;         const float sp = xx > 20.f ? xx : log1pf(expf(xx));
	v_mul_f32_e32 v1, 0x3fb8aa3b, v0
	v_rndne_f32_e32 v2, v1
	s_mov_b32 s4, 0x3fb8aa3b
	v_sub_f32_e32 v3, v1, v2
	v_fma_f32 v1, v0, s4, -v1
	v_fmac_f32_e32 v1, 0x32a5705f, v0
	v_add_f32_e32 v1, v3, v1
	v_cvt_i32_f32_e32 v2, v2
	v_exp_f32_e32 v1, v1
	s_mov_b32 s4, 0xc2ce8ed0
	v_cmp_ngt_f32_e32 vcc, s4, v0
	s_mov_b32 s4, 0x42b17218
	v_ldexp_f32 v1, v1, v2
	v_cndmask_b32_e32 v1, 0, v1, vcc
	v_cmp_nlt_f32_e32 vcc, s4, v0
	s_mov_b32 s4, 0x3f2aaaab
	s_nop 0
	v_cndmask_b32_e32 v14, v245, v1, vcc
	v_add_f32_e32 v2, 1.0, v14
	v_add_f32_e32 v0, -1.0, v2
	v_sub_f32_e32 v1, v0, v2
	v_add_f32_e32 v1, 1.0, v1
	v_sub_f32_e32 v0, v14, v0
	v_add_f32_e32 v3, v0, v1
	v_frexp_mant_f32_e32 v4, v2
	v_cvt_f64_f32_e32 v[0:1], v2
	v_frexp_exp_i32_f64_e32 v0, v[0:1]
	v_cmp_gt_f32_e32 vcc, s4, v4
	s_mov_b32 s4, 0x3f317218
	s_nop 0
	v_subbrev_co_u32_e32 v8, vcc, 0, v0, vcc
	v_sub_u32_e32 v0, 0, v8
	v_ldexp_f32 v1, v2, v0
	v_add_f32_e32 v2, -1.0, v1
	v_add_f32_e32 v4, 1.0, v1
	v_ldexp_f32 v0, v3, v0
	v_add_f32_e32 v3, 1.0, v2
	v_add_f32_e32 v5, -1.0, v4
	v_sub_f32_e32 v3, v1, v3
	v_sub_f32_e32 v1, v1, v5
	v_add_f32_e32 v3, v0, v3
	v_add_f32_e32 v0, v0, v1
	v_add_f32_e32 v9, v4, v0
	v_rcp_f32_e32 v11, v9
	v_sub_f32_e32 v1, v4, v9
	v_add_f32_e32 v10, v0, v1
	v_add_f32_e32 v1, v2, v3
	v_mul_f32_e32 v13, v1, v11
	v_sub_f32_e32 v0, v2, v1
	v_mul_f32_e32 v2, v9, v13
	v_fma_f32 v4, v13, v9, -v2
	v_fmac_f32_e32 v4, v13, v10
	v_add_f32_e32 v12, v3, v0
	v_add_f32_e32 v0, v2, v4
	v_sub_f32_e32 v3, v1, v0
	v_pk_add_f32 v[6:7], v[0:1], v[2:3] neg_lo:[0,1] neg_hi:[0,1]
	v_mov_b32_e32 v5, v0
	v_pk_add_f32 v[0:1], v[6:7], v[4:5] neg_lo:[0,1] neg_hi:[0,1]
	v_cmp_neq_f32_e32 vcc, s85, v14
	v_add_f32_e32 v1, v12, v1
	v_add_f32_e32 v0, v0, v1
	v_add_f32_e32 v1, v3, v0
	v_mul_f32_e32 v12, v11, v1
	v_mul_f32_e32 v2, v9, v12
	v_fma_f32 v4, v12, v9, -v2
	v_fmac_f32_e32 v4, v12, v10
	v_sub_f32_e32 v3, v3, v1
	v_add_f32_e32 v9, v0, v3
	v_add_f32_e32 v0, v2, v4
	v_sub_f32_e32 v3, v1, v0
	v_pk_add_f32 v[6:7], v[0:1], v[2:3] neg_lo:[0,1] neg_hi:[0,1]
	v_mov_b32_e32 v5, v0
	v_pk_add_f32 v[0:1], v[6:7], v[4:5] neg_lo:[0,1] neg_hi:[0,1]
	s_nop 0
	v_add_f32_e32 v1, v9, v1
	v_add_f32_e32 v0, v0, v1
	v_add_f32_e32 v1, v13, v12
	v_add_f32_e32 v0, v3, v0
	v_sub_f32_e32 v2, v1, v13
	v_mul_f32_e32 v0, v11, v0
	v_sub_f32_e32 v2, v12, v2
	v_add_f32_e32 v2, v2, v0
	v_add_f32_e32 v4, v1, v2
	v_mul_f32_e32 v5, v4, v4
	v_mov_b32_e32 v0, 0x3ecc95a3
	v_fmamk_f32 v0, v5, 0x3e9b6dac, v0
	v_fmaak_f32 v215, v5, v0, 0x3f2aaada
	v_cvt_f32_i32_e32 v0, v8
	v_sub_f32_e32 v1, v4, v1
	v_sub_f32_e32 v1, v2, v1
	v_ldexp_f32 v6, v1, 1
	v_mul_f32_e32 v1, v4, v5
	v_ldexp_f32 v3, v4, 1
	v_pk_mul_f32 v[4:5], v[0:1], v[214:215]
	s_nop 0
	v_fma_f32 v2, v0, s4, -v4
	v_fmac_f32_e32 v2, 0xb102e308, v0
	v_pk_add_f32 v[0:1], v[4:5], v[2:3]
	s_mov_b32 s4, 0x33800000
	v_sub_f32_e32 v3, v1, v3
	v_sub_f32_e32 v3, v5, v3
	v_add_f32_e32 v7, v6, v3
	v_mov_b32_e32 v6, v4
	v_pk_add_f32 v[4:5], v[0:1], v[4:5] neg_lo:[0,1] neg_hi:[0,1]
	v_pk_add_f32 v[8:9], v[0:1], v[6:7]
	v_mov_b32_e32 v3, v0
	v_mov_b32_e32 v5, v9
	v_pk_add_f32 v[10:11], v[2:3], v[4:5] neg_lo:[0,1] neg_hi:[0,1]
	v_pk_add_f32 v[2:3], v[2:3], v[4:5]
	v_mov_b32_e32 v6, v7
	v_pk_add_f32 v[4:5], v[2:3], v[0:1] op_sel:[1,0] op_sel_hi:[0,1] neg_lo:[0,1] neg_hi:[0,1]
	v_pk_add_f32 v[12:13], v[8:9], v[4:5] op_sel_hi:[1,0] neg_lo:[0,1] neg_hi:[0,1]
	v_mov_b32_e32 v8, v9
	v_mov_b32_e32 v9, v3
	v_pk_mov_b32 v[4:5], v[0:1], v[4:5] op_sel:[1,0]
	v_mov_b32_e32 v7, v0
	v_pk_add_f32 v[4:5], v[8:9], v[4:5] neg_lo:[0,1] neg_hi:[0,1]
	v_mov_b32_e32 v12, v10
	v_pk_add_f32 v[0:1], v[6:7], v[4:5] neg_lo:[0,1] neg_hi:[0,1]
	v_mov_b32_e32 v11, v3
	v_pk_add_f32 v[4:5], v[12:13], v[0:1]
	s_nop 0
	v_pk_add_f32 v[6:7], v[4:5], v[4:5] op_sel:[0,1] op_sel_hi:[1,0]
	s_nop 0
	v_pk_add_f32 v[2:3], v[2:3], v[6:7] op_sel:[1,0] op_sel_hi:[0,1]
	v_mov_b32_e32 v5, v2
	v_pk_add_f32 v[8:9], v[4:5], v[10:11] neg_lo:[0,1] neg_hi:[0,1]
	v_mov_b32_e32 v1, v6
	v_sub_f32_e32 v3, v4, v8
	v_pk_add_f32 v[0:1], v[0:1], v[8:9] neg_lo:[0,1] neg_hi:[0,1]
	v_sub_f32_e32 v3, v10, v3
	v_add_f32_e32 v0, v0, v3
	v_add_f32_e32 v0, v0, v1
	v_add_f32_e32 v0, v2, v0
	v_cndmask_b32_e32 v0, v245, v0, vcc
	v_cmp_lt_f32_e64 vcc, |v14|, s4
	s_nop 1
	v_cndmask_b32_e32 v0, v0, v14, vcc
; DI void gdn_prep_item(const Args& a, int l, int bh, int n, LAS unsigned char* lds, const int tidx, const int xf) {
;     ...
;         float g = -expf(a.gdn_a_log[l * NH + h]) * sp;
;         const float beta = 1.f / (1.f + expf(-bv));
; #pragma unroll
;         for (int o = 1; o < 64; o <<= 1) { const float y = __shfl_up(g, o); if (lane >= o) g += y; }
;         const float eg = __expf(g), gl = __shfl(g, 63);
;         gcs[tid] = g; bts[tid] = beta; bes[tid] = beta * eg; kds[tid] = __expf(gl - g); egs[tid] = eg;
;         if (tid == 63) egl[bh * 64 + n] = expf(g);
.LBB0_422:
	s_or_b64 exec, exec, s[26:27]
	s_add_u32 s4, s70, s24
	s_addc_u32 s5, s71, s25
	v_mov_b32_e32 v1, v201
	s_mov_b32 s4, 0x3fb8aa3b
	s_waitcnt vmcnt(0)
	v_mul_f32_e32 v2, 0x3fb8aa3b, v1
	v_fma_f32 v3, v1, s4, -v2
	v_rndne_f32_e32 v4, v2
	v_fmac_f32_e32 v3, 0x32a5705f, v1
	v_sub_f32_e32 v2, v2, v4
	v_add_f32_e32 v2, v2, v3
	v_exp_f32_e32 v2, v2
	v_cvt_i32_f32_e32 v3, v4
	s_mov_b32 s4, 0xc2ce8ed0
	v_cmp_ngt_f32_e32 vcc, s4, v1
	s_mov_b32 s4, 0x42b17218
	v_ldexp_f32 v2, v2, v3
	v_mul_f32_e32 v3, 0xbfb8aa3b, v195
	v_rndne_f32_e32 v4, v3
	v_sub_f32_e32 v5, v3, v4
	v_fma_f32 v3, v195, s3, -v3
	v_fmac_f32_e32 v3, 0xb2a5705f, v195
	v_add_f32_e32 v3, v5, v3
	v_exp_f32_e32 v3, v3
	v_cvt_i32_f32_e32 v4, v4
	v_cndmask_b32_e32 v2, 0, v2, vcc
	v_cmp_nlt_f32_e32 vcc, s4, v1
	s_mov_b32 s4, 0x42ce8ed0
	v_ldexp_f32 v3, v3, v4
	v_cndmask_b32_e32 v1, v245, v2, vcc
	v_cmp_nlt_f32_e32 vcc, s4, v195
	s_mov_b32 s4, 0xc2b17218
	v_and_b32_e32 v4, 64, v246
	v_cndmask_b32_e32 v3, 0, v3, vcc
	v_cmp_ngt_f32_e32 vcc, s4, v195
	v_add_u32_e32 v5, -1, v246
	v_mul_f32_e64 v2, v0, -v1
	v_cndmask_b32_e32 v3, v245, v3, vcc
	v_cmp_lt_i32_e32 vcc, v5, v4
	v_readlane_b32 s4, v254, 38
	v_readlane_b32 s5, v254, 39
	v_cndmask_b32_e32 v5, v5, v246, vcc
	v_lshlrev_b32_e32 v5, 2, v5
	ds_bpermute_b32 v5, v5, v2
	v_add_f32_e32 v3, 1.0, v3
	s_waitcnt lgkmcnt(0)
	v_fma_f32 v0, v0, -v1, v5
	v_add_u32_e32 v1, -2, v246
	v_cmp_lt_i32_e32 vcc, v1, v4
	v_cndmask_b32_e64 v0, v0, v2, s[4:5]
	v_readlane_b32 s4, v254, 40
	v_cndmask_b32_e32 v1, v1, v246, vcc
	v_lshlrev_b32_e32 v1, 2, v1
	ds_bpermute_b32 v1, v1, v0
	v_readlane_b32 s5, v254, 41
	s_waitcnt lgkmcnt(0)
	v_add_f32_e32 v1, v0, v1
	v_cndmask_b32_e64 v0, v1, v0, s[4:5]
	v_add_u32_e32 v1, -4, v246
	v_cmp_lt_i32_e32 vcc, v1, v4
	v_readlane_b32 s4, v254, 42
	v_readlane_b32 s5, v254, 43
	v_cndmask_b32_e32 v1, v1, v246, vcc
	v_lshlrev_b32_e32 v1, 2, v1
	ds_bpermute_b32 v1, v1, v0
	s_waitcnt lgkmcnt(0)
	v_add_f32_e32 v1, v0, v1
	v_cndmask_b32_e64 v0, v1, v0, s[4:5]
	v_add_u32_e32 v1, -8, v246
	v_cmp_lt_i32_e32 vcc, v1, v4
	v_readlane_b32 s4, v254, 44
	v_readlane_b32 s5, v254, 45
	v_cndmask_b32_e32 v1, v1, v246, vcc
	v_lshlrev_b32_e32 v1, 2, v1
	ds_bpermute_b32 v1, v1, v0
	s_waitcnt lgkmcnt(0)
	v_add_f32_e32 v1, v0, v1
	v_cndmask_b32_e64 v0, v1, v0, s[4:5]
	v_add_u32_e32 v1, -16, v246
	v_cmp_lt_i32_e32 vcc, v1, v4
	v_readlane_b32 s4, v254, 46
	v_readlane_b32 s5, v254, 47
	v_cndmask_b32_e32 v1, v1, v246, vcc
	v_lshlrev_b32_e32 v1, 2, v1
	ds_bpermute_b32 v1, v1, v0
	s_waitcnt lgkmcnt(0)
	v_add_f32_e32 v1, v0, v1
	v_cndmask_b32_e64 v1, v1, v0, s[4:5]
	v_subrev_u32_e32 v0, 32, v246
	v_div_scale_f32 v2, s[4:5], v3, v3, 1.0
	v_cmp_lt_i32_e32 vcc, v0, v4
	v_rcp_f32_e32 v4, v2
	v_readlane_b32 s4, v254, 48
	v_cndmask_b32_e32 v0, v0, v246, vcc
	v_lshlrev_b32_e32 v0, 2, v0
	ds_bpermute_b32 v0, v0, v1
	v_fma_f32 v5, -v2, v4, 1.0
	v_fmac_f32_e32 v4, v5, v4
	v_div_scale_f32 v5, vcc, 1.0, v3, 1.0
	v_mul_f32_e32 v6, v5, v4
	v_fma_f32 v7, -v2, v6, v5
	s_waitcnt lgkmcnt(0)
	v_add_f32_e32 v0, v1, v0
	v_fmac_f32_e32 v6, v7, v4
	v_cndmask_b32_e64 v1, v0, v1, s[50:51]
	v_fma_f32 v2, -v2, v6, v5
	v_div_fmas_f32 v2, v2, v4, v6
	ds_bpermute_b32 v4, v247, v1
	v_div_fixup_f32 v2, v2, v3, 1.0
	v_lshl_add_u32 v5, v220, 2, v194
	v_mul_f32_e32 v3, 0x3fb8aa3b, v1
	ds_write2st64_b32 v5, v1, v2 offset0:136 offset1:137
	s_waitcnt lgkmcnt(1)
	v_sub_f32_e32 v1, v4, v1
	v_exp_f32_e32 v3, v3
	v_mul_f32_e32 v1, 0x3fb8aa3b, v1
	v_exp_f32_e32 v1, v1
	v_readlane_b32 s5, v254, 49
	v_mul_f32_e32 v2, v2, v3
	ds_write2st64_b32 v5, v2, v1 offset0:138 offset1:139
	ds_write_b32 v5, v3 offset:35840
	s_and_b64 exec, exec, s[4:5]
	s_cbranch_execz .LBB0_424
	v_mul_f32_e32 v1, 0x3fb8aa3b, v0
	v_rndne_f32_e32 v2, v1
	s_mov_b32 s4, 0x3fb8aa3b
	v_sub_f32_e32 v3, v1, v2
	v_fma_f32 v1, v0, s4, -v1
	v_fmac_f32_e32 v1, 0x32a5705f, v0
	v_add_f32_e32 v1, v3, v1
	v_cvt_i32_f32_e32 v2, v2
	v_exp_f32_e32 v1, v1
	s_mov_b32 s4, 0xc2ce8ed0
	v_cmp_ngt_f32_e32 vcc, s4, v0
	s_mov_b32 s4, 0x42b17218
	v_ldexp_f32 v1, v1, v2
	v_cndmask_b32_e32 v1, 0, v1, vcc
	v_cmp_nlt_f32_e32 vcc, s4, v0
	s_add_u32 s4, s91, s94
	s_addc_u32 s5, s34, s95
	v_cndmask_b32_e32 v0, v245, v1, vcc
	global_store_dword v205, v0, s[4:5]

; __global__ void __launch_bounds__(512, 2) hybrid_fwd(Args a0) {
	.amdhsa_kernel _Z10hybrid_fwd4Args
		.amdhsa_group_segment_fixed_size 0
		.amdhsa_private_segment_fixed_size 0
		.amdhsa_kernarg_size 392
		.amdhsa_user_sgpr_count 2
		.amdhsa_user_sgpr_dispatch_ptr 0
		.amdhsa_user_sgpr_queue_ptr 0
		.amdhsa_user_sgpr_kernarg_segment_ptr 1
		.amdhsa_user_sgpr_dispatch_id 0
		.amdhsa_user_sgpr_kernarg_preload_length 0
		.amdhsa_user_sgpr_kernarg_preload_offset 0
		.amdhsa_user_sgpr_private_segment_size 0
		.amdhsa_uses_dynamic_stack 0
		.amdhsa_enable_private_segment 0
		.amdhsa_system_sgpr_workgroup_id_x 1
		.amdhsa_system_sgpr_workgroup_id_y 0
		.amdhsa_system_sgpr_workgroup_id_z 0
		.amdhsa_system_sgpr_workgroup_info 0
		.amdhsa_system_vgpr_workitem_id 2
		.amdhsa_next_free_vgpr 256
		.amdhsa_next_free_sgpr 102
		.amdhsa_accum_offset 256
		.amdhsa_reserve_vcc 1
		.amdhsa_float_round_mode_32 0
		.amdhsa_float_round_mode_16_64 0
		.amdhsa_float_denorm_mode_32 3
		.amdhsa_float_denorm_mode_16_64 3
		.amdhsa_dx10_clamp 1
		.amdhsa_ieee_mode 1
		.amdhsa_fp16_overflow 0
		.amdhsa_tg_split 0
		.amdhsa_exception_fp_ieee_invalid_op 0
		.amdhsa_exception_fp_denorm_src 0
		.amdhsa_exception_fp_ieee_div_zero 0
		.amdhsa_exception_fp_ieee_overflow 0
		.amdhsa_exception_fp_ieee_underflow 0
		.amdhsa_exception_fp_ieee_inexact 0
		.amdhsa_exception_int_div_zero 0
	.end_amdhsa_kernel

; __global__ void __launch_bounds__(512, 2) hybrid_fwd(Args a0) {
amdhsa.kernels:
  - .agpr_count:     0
    .args:
      - .offset:         0
        .size:           136
        .value_kind:     by_value
      - .offset:         136
        .size:           4
        .value_kind:     hidden_block_count_x
      - .offset:         140
        .size:           4
        .value_kind:     hidden_block_count_y
      - .offset:         144
        .size:           4
        .value_kind:     hidden_block_count_z
      - .offset:         148
        .size:           2
        .value_kind:     hidden_group_size_x
      - .offset:         150
        .size:           2
        .value_kind:     hidden_group_size_y
      - .offset:         152
        .size:           2
        .value_kind:     hidden_group_size_z
      - .offset:         154
        .size:           2
        .value_kind:     hidden_remainder_x
      - .offset:         156
        .size:           2
        .value_kind:     hidden_remainder_y
      - .offset:         158
        .size:           2
        .value_kind:     hidden_remainder_z
      - .offset:         176
        .size:           8
        .value_kind:     hidden_global_offset_x
      - .offset:         184
        .size:           8
        .value_kind:     hidden_global_offset_y
      - .offset:         192
        .size:           8
        .value_kind:     hidden_global_offset_z
      - .offset:         200
        .size:           2
        .value_kind:     hidden_grid_dims
      - .offset:         224
        .size:           8
        .value_kind:     hidden_multigrid_sync_arg
      - .offset:         256
        .size:           4
        .value_kind:     hidden_dynamic_lds_size
    .group_segment_fixed_size: 0
    .kernarg_segment_align: 8
    .kernarg_segment_size: 392
    .language:       OpenCL C
    .language_version:
      - 2
      - 0
    .max_flat_workgroup_size: 512
    .name:           _Z10hybrid_fwd4Args
    .private_segment_fixed_size: 0
    .sgpr_count:     108
    .sgpr_spill_count: 248
    .symbol:         _Z10hybrid_fwd4Args.kd
    .uniform_work_group_size: 1
    .uses_dynamic_stack: false
    .vgpr_count:     256
    .vgpr_spill_count: 0
    .wavefront_size: 64
